# lnffn (layer 1): gate vector loaded at the top of each row into AGPRs
# baseline (speedup 1.0000x reference)
.LBB0_1650:
	s_waitcnt vmcnt(0)
	v_add_u32_e32 v9, 0xffffe000, v8
	v_lshrrev_b32_e32 v9, 11, v9
	v_readlane_b32 s24, v126, 2
	v_add_u32_e32 v9, 6, v9
	v_readlane_b32 s30, v126, 8
	v_readlane_b32 s31, v126, 9
	v_cndmask_b32_e64 v9, 5, v9, s[0:1]
	v_mov_b32_e32 v29, v1
	v_mov_b64_e32 v[62:63], s[30:31]
	v_mad_u64_u32 v[62:63], s[0:1], v9, s22, v[62:63]
	v_lshl_add_u64 v[88:89], v[62:63], 0, s[10:11]
	v_lshl_add_u64 v[62:63], v[88:89], 0, v[0:1]
	v_lshl_add_u64 v[80:81], v[88:89], 0, v[28:29]
	v_mov_b32_e32 v31, v1
	v_accvgpr_read_b32 v62, a40
	v_accvgpr_read_b32 v63, a41
	v_accvgpr_read_b32 v64, a42
	v_accvgpr_read_b32 v65, a43
	s_nop 0
	v_accvgpr_read_b32 v80, a44
	v_accvgpr_read_b32 v81, a45
	v_accvgpr_read_b32 v82, a46
	v_accvgpr_read_b32 v83, a47
	v_lshl_add_u64 v[84:85], v[88:89], 0, v[30:31]
	v_accvgpr_read_b32 v84, a48
	v_accvgpr_read_b32 v85, a49
	v_accvgpr_read_b32 v86, a50
	v_accvgpr_read_b32 v87, a51
	v_mov_b32_e32 v33, v1
	v_lshl_add_u64 v[88:89], v[88:89], 0, v[32:33]
	v_accvgpr_read_b32 v88, a52
	v_accvgpr_read_b32 v89, a53
	v_accvgpr_read_b32 v90, a54
	v_accvgpr_read_b32 v91, a55
	v_lshlrev_b32_e32 v92, 16, v42
	v_and_b32_e32 v93, 0xffff0000, v42
	v_lshlrev_b32_e32 v42, 16, v43
	v_and_b32_e32 v43, 0xffff0000, v43
	v_lshlrev_b32_e32 v94, 16, v40
	v_and_b32_e32 v95, 0xffff0000, v40
	v_lshlrev_b32_e32 v96, 16, v41
	v_and_b32_e32 v97, 0xffff0000, v41
	v_lshlrev_b32_e32 v100, 16, v36
	v_and_b32_e32 v101, 0xffff0000, v36
	v_lshlrev_b32_e32 v102, 16, v37
	v_and_b32_e32 v103, 0xffff0000, v37
	v_lshlrev_b32_e32 v98, 16, v38
	v_and_b32_e32 v99, 0xffff0000, v38
	v_lshlrev_b32_e32 v38, 16, v39
	v_and_b32_e32 v39, 0xffff0000, v39
	s_and_b64 s[14:15], exec, vcc
	s_or_b64 s[8:9], s[14:15], s[8:9]
	v_readlane_b32 s25, v126, 3
	v_readlane_b32 s26, v126, 4
	v_readlane_b32 s27, v126, 5
	v_readlane_b32 s28, v126, 6
	v_readlane_b32 s29, v126, 7
	s_waitcnt vmcnt(3)
	v_pk_mul_f32 v[36:37], v[58:59], v[64:65]
	v_pk_mul_f32 v[40:41], v[56:57], v[62:63]
	s_waitcnt vmcnt(2)
	v_pk_mul_f32 v[54:55], v[54:55], v[82:83]
	v_pk_mul_f32 v[52:53], v[52:53], v[80:81]
	s_waitcnt vmcnt(1)
	v_pk_mul_f32 v[56:57], v[50:51], v[86:87]
	v_pk_mul_f32 v[58:59], v[48:49], v[84:85]
	v_pk_fma_f32 v[48:49], v[92:93], s[12:13], v[40:41] op_sel_hi:[1,0,1]
	v_pk_fma_f32 v[50:51], v[42:43], s[12:13], v[36:37] op_sel_hi:[1,0,1]
	v_pk_fma_f32 v[40:41], v[94:95], s[12:13], v[52:53] op_sel_hi:[1,0,1]
	v_pk_fma_f32 v[42:43], v[96:97], s[12:13], v[54:55] op_sel_hi:[1,0,1]
	v_pk_fma_f32 v[38:39], v[38:39], s[12:13], v[56:57] op_sel_hi:[1,0,1]
	v_pk_fma_f32 v[36:37], v[98:99], s[12:13], v[58:59] op_sel_hi:[1,0,1]
	v_pk_mov_b32 v[52:53], v[48:49], v[50:51] op_sel:[1,0]
	v_mov_b32_e32 v54, v48
	v_mov_b32_e32 v55, v51
	v_pk_mov_b32 v[56:57], v[40:41], v[42:43] op_sel:[1,0]
	v_mov_b32_e32 v58, v40
	v_mov_b32_e32 v59, v43
	s_waitcnt vmcnt(0)
	v_pk_mul_f32 v[44:45], v[44:45], v[90:91]
	v_pk_mul_f32 v[46:47], v[46:47], v[88:89]
	v_pk_add_f32 v[52:53], v[52:53], v[54:55]
	v_pk_add_f32 v[54:55], v[56:57], v[58:59]
	v_pk_fma_f32 v[44:45], v[102:103], s[12:13], v[44:45] op_sel_hi:[1,0,1]
	v_pk_fma_f32 v[46:47], v[100:101], s[12:13], v[46:47] op_sel_hi:[1,0,1]
	v_add_f32_e32 v9, v52, v53
	v_pk_add_f32 v[52:53], v[54:55], v[54:55] op_sel:[0,1] op_sel_hi:[1,0]
	v_add_f32_e32 v62, v36, v37
	v_add_f32_e32 v64, v38, v39
	v_mov_b32_e32 v81, v46
	v_mov_b32_e32 v63, v44
	v_mov_b32_e32 v65, v45
	v_add_f32_e32 v80, 0, v9
	v_mov_b32_e32 v53, v47
	v_pk_add_f32 v[56:57], v[62:63], v[64:65]
	v_pk_add_f32 v[52:53], v[80:81], v[52:53]
	s_nop 0
	v_pk_add_f32 v[52:53], v[52:53], v[56:57]
	s_nop 0
	v_add_f32_e32 v9, v52, v53
	v_mov_b32_e32 v29, v9
	s_nop 1
	v_add_f32_dpp v29, v29, v29 quad_perm:[1,0,3,2] row_mask:0xf bank_mask:0xf
	s_nop 1
	v_add_f32_dpp v29, v29, v29 quad_perm:[2,3,0,1] row_mask:0xf bank_mask:0xf
	s_nop 1
	v_add_f32_dpp v29, v29, v29 row_half_mirror row_mask:0xf bank_mask:0xf
	s_nop 1
	v_add_f32_dpp v29, v29, v29 row_mirror row_mask:0xf bank_mask:0xf
	s_nop 0
	v_readlane_b32 s44, v29, 0
	v_readlane_b32 s45, v29, 16
	v_readlane_b32 s46, v29, 32
	v_readlane_b32 s47, v29, 48
	s_nop 1
	v_mov_b32_e32 v29, s44
	v_add_f32_e32 v29, s45, v29
	v_add_f32_e32 v29, s46, v29
	v_add_f32_e32 v29, s47, v29
	s_nop 1
	v_accvgpr_read_b32 v52, a8
	v_accvgpr_read_b32 v53, a9
	v_accvgpr_read_b32 v54, a10
	v_accvgpr_read_b32 v55, a11
	s_nop 1
	v_accvgpr_read_b32 v56, a12
	v_accvgpr_read_b32 v57, a13
	v_accvgpr_read_b32 v58, a14
	v_accvgpr_read_b32 v59, a15
	v_mov_b32_e32 v9, v29
	v_fmamk_f32 v49, v9, 0xba800000, v49
	v_fmac_f32_e32 v48, 0xba800000, v9
	v_fmamk_f32 v51, v9, 0xba800000, v51
	v_fmac_f32_e32 v50, 0xba800000, v9
	v_fmamk_f32 v41, v9, 0xba800000, v41
	v_fmac_f32_e32 v40, 0xba800000, v9
	v_fmamk_f32 v43, v9, 0xba800000, v43
	v_fmac_f32_e32 v42, 0xba800000, v9
	v_pk_mul_f32 v[62:63], v[50:51], v[50:51]
	v_pk_mul_f32 v[64:65], v[48:49], v[48:49]
	v_pk_mul_f32 v[80:81], v[42:43], v[42:43]
	v_pk_mul_f32 v[82:83], v[40:41], v[40:41]
	v_fmac_f32_e32 v36, 0xba800000, v9
	v_fmac_f32_e32 v38, 0xba800000, v9
	v_pk_mov_b32 v[86:87], v[64:65], v[62:63] op_sel:[1,0]
	v_mov_b32_e32 v65, v63
	v_pk_mov_b32 v[62:63], v[82:83], v[80:81] op_sel:[1,0]
	v_mov_b32_e32 v83, v81
	v_fmamk_f32 v37, v9, 0xba800000, v37
	v_fmamk_f32 v39, v9, 0xba800000, v39
	v_mul_f32_e32 v60, v36, v36
	v_mul_f32_e32 v84, v38, v38
	v_pk_add_f32 v[64:65], v[86:87], v[64:65]
	v_pk_add_f32 v[62:63], v[62:63], v[82:83]
	v_fmamk_f32 v45, v9, 0xba800000, v45
	v_fmac_f32_e32 v44, 0xba800000, v9
	v_fmamk_f32 v47, v9, 0xba800000, v47
	v_fmac_f32_e32 v46, 0xba800000, v9
	v_pk_fma_f32 v[80:81], v[36:37], v[36:37], v[60:61] op_sel_hi:[1,1,0]
	v_pk_fma_f32 v[84:85], v[38:39], v[38:39], v[84:85] op_sel_hi:[1,1,0]
	v_pk_add_f32 v[64:65], v[64:65], v[64:65] op_sel_hi:[0,1]
	v_pk_add_f32 v[62:63], v[62:63], v[62:63] op_sel_hi:[0,1]
	v_mul_f32_e32 v80, v46, v46
	v_mul_f32_e32 v84, v47, v47
	v_mul_f32_e32 v64, v44, v44
	v_mul_f32_e32 v62, v45, v45
	v_pk_add_f32 v[80:81], v[80:81], v[84:85]
	v_pk_add_f32 v[62:63], v[64:65], v[62:63]
	s_nop 0
	v_pk_add_f32 v[62:63], v[80:81], v[62:63]
	s_nop 0
	v_add_f32_e32 v9, v62, v63
	v_mov_b32_e32 v29, v9
	s_nop 1
	v_add_f32_dpp v29, v29, v29 quad_perm:[1,0,3,2] row_mask:0xf bank_mask:0xf
	s_nop 1
	v_add_f32_dpp v29, v29, v29 quad_perm:[2,3,0,1] row_mask:0xf bank_mask:0xf
	s_nop 1
	v_add_f32_dpp v29, v29, v29 row_half_mirror row_mask:0xf bank_mask:0xf
	s_nop 1
	v_add_f32_dpp v29, v29, v29 row_mirror row_mask:0xf bank_mask:0xf
	s_nop 0
	v_readlane_b32 s44, v29, 0
	v_readlane_b32 s45, v29, 16
	v_readlane_b32 s46, v29, 32
	v_readlane_b32 s47, v29, 48
	s_nop 1
	v_mov_b32_e32 v29, s44
	v_add_f32_e32 v29, s45, v29
	v_add_f32_e32 v29, s46, v29
	v_add_f32_e32 v29, s47, v29
	v_mov_b32_e32 v9, v29
	v_fmamk_f32 v9, v9, 0x3a800000, v71
	v_mul_f32_e32 v29, 0x4b800000, v9
	v_cmp_gt_f32_e32 vcc, s23, v9
	s_nop 1
	v_cndmask_b32_e32 v9, v9, v29, vcc
	v_rsq_f32_e32 v29, v9
	v_ashrrev_i32_e32 v9, 31, v8
	v_lshlrev_b64 v[8:9], 12, v[8:9]
	v_lshl_add_u64 v[62:63], v[26:27], 0, v[8:9]
	v_mul_f32_e32 v8, 0x45800000, v29
	v_cndmask_b32_e32 v8, v29, v8, vcc
	v_pk_mul_f32 v[48:49], v[48:49], v[8:9] op_sel_hi:[1,0]
	v_pk_mul_f32 v[50:51], v[50:51], v[8:9] op_sel_hi:[1,0]
	v_pk_fma_f32 v[48:49], v[52:53], v[48:49], v[56:57]
	v_pk_fma_f32 v[50:51], v[54:55], v[50:51], v[58:59]
	global_store_dwordx4 v[62:63], v[48:51], off
	s_nop 1
	v_accvgpr_read_b32 v48, a16
	v_accvgpr_read_b32 v49, a17
	v_accvgpr_read_b32 v50, a18
	v_accvgpr_read_b32 v51, a19
	s_nop 0
	s_nop 1
	v_accvgpr_read_b32 v52, a20
	v_accvgpr_read_b32 v53, a21
	v_accvgpr_read_b32 v54, a22
	v_accvgpr_read_b32 v55, a23
	v_pk_mul_f32 v[42:43], v[42:43], v[8:9] op_sel_hi:[1,0]
	v_pk_mul_f32 v[40:41], v[40:41], v[8:9] op_sel_hi:[1,0]
	v_pk_mul_f32 v[38:39], v[38:39], v[8:9] op_sel_hi:[1,0]
	v_pk_mul_f32 v[36:37], v[36:37], v[8:9] op_sel_hi:[1,0]
	v_mov_b32_e32 v9, v35
	v_pk_mul_f32 v[56:57], v[44:45], v[8:9] op_sel_hi:[1,0]
	v_pk_mul_f32 v[44:45], v[46:47], v[8:9] op_sel_hi:[1,0]
	v_mov_b32_e32 v8, v34
	v_pk_fma_f32 v[40:41], v[48:49], v[40:41], v[52:53]
	v_pk_fma_f32 v[42:43], v[50:51], v[42:43], v[54:55]
	global_store_dwordx4 v[62:63], v[40:43], off offset:1024
	s_nop 1
	v_accvgpr_read_b32 v40, a24
	v_accvgpr_read_b32 v41, a25
	v_accvgpr_read_b32 v42, a26
	v_accvgpr_read_b32 v43, a27
	s_nop 0
	s_nop 1
	v_accvgpr_read_b32 v48, a28
	v_accvgpr_read_b32 v49, a29
	v_accvgpr_read_b32 v50, a30
	v_accvgpr_read_b32 v51, a31
	v_pk_fma_f32 v[36:37], v[40:41], v[36:37], v[48:49]
	v_pk_fma_f32 v[38:39], v[42:43], v[38:39], v[50:51]
	global_store_dwordx4 v[62:63], v[36:39], off offset:2048
	s_nop 1
	v_accvgpr_read_b32 v48, a32
	v_accvgpr_read_b32 v49, a33
	v_accvgpr_read_b32 v50, a34
	v_accvgpr_read_b32 v51, a35
	s_nop 1
	v_accvgpr_read_b32 v52, a36
	v_accvgpr_read_b32 v53, a37
	v_accvgpr_read_b32 v54, a38
	v_accvgpr_read_b32 v55, a39
	v_mov_b64_e32 v[42:43], v[72:73]
	v_mov_b64_e32 v[40:41], v[74:75]
	v_mov_b64_e32 v[38:39], v[76:77]
	v_mov_b64_e32 v[36:37], v[78:79]
	v_pk_fma_f32 v[44:45], v[48:49], v[44:45], v[52:53]
	v_pk_fma_f32 v[46:47], v[50:51], v[56:57], v[54:55]
	global_store_dwordx4 v[62:63], v[44:47], off offset:3072
	s_andn2_b64 exec, exec, s[8:9]
	s_cbranch_execz .LBB0_1656
.LBB0_1651:
	v_readfirstlane_b32 s58, v8
	v_readlane_b32 s60, v126, 8
	v_readlane_b32 s61, v126, 9
	s_sub_i32 s59, s58, 0x2000
	s_ashr_i32 s59, s59, 11
	s_add_i32 s59, s59, 1
	s_cmp_lt_i32 s58, 0x2000
	s_cselect_b32 s59, 0, s59
	s_mul_i32 s59, s59, 0x6000
	s_add_u32 s60, s60, 0x18ea3000
	s_addc_u32 s61, s61, 0
	s_add_u32 s60, s60, s59
	s_addc_u32 s61, s61, 0
	global_load_dwordx4 a[40:43], v0, s[60:61]
	global_load_dwordx4 a[44:47], v0, s[60:61] offset:1024
	global_load_dwordx4 a[48:51], v0, s[60:61] offset:2048
	global_load_dwordx4 a[52:55], v0, s[60:61] offset:3072
	v_add_u32_e32 v34, s19, v8
	v_cmp_gt_i32_e64 s[0:1], s18, v34
	v_cmp_lt_i32_e32 vcc, s20, v34
	s_and_saveexec_b64 s[14:15], s[0:1]
	s_cbranch_execz .LBB0_1653
	v_ashrrev_i32_e32 v35, 31, v34
	v_lshlrev_b64 v[44:45], 6, v[34:35]
	v_lshl_add_u64 v[44:45], v[2:3], 0, v[44:45]
	v_lshlrev_b64 v[46:47], 11, v[34:35]
	v_lshl_add_u64 v[46:47], v[4:5], 0, v[46:47]
	global_load_dword v35, v[44:45], off
	global_load_dwordx2 v[72:73], v[46:47], off
	global_load_dwordx2 v[74:75], v[46:47], off offset:512
	global_load_dwordx2 v[76:77], v[46:47], off offset:1024
	global_load_dwordx2 v[78:79], v[46:47], off offset:1536
